# hand-written grid barrier release: XCC leaders post one add to 16 per-XCC copies of the release counter; workgroups poll their own XCC copy
# speedup vs baseline: 1.1801x; 1.0164x over previous
.LBB0_6:
	v_readlane_b32 s0, v242, 1
	v_readlane_b32 s1, v242, 2
	s_load_dword s4, s[0:1], 0x118
	v_mov_b32_e32 v1, 0x12c0
	s_mov_b32 s79, 0
	s_mul_i32 s18, s76, 12
	v_mov_b32_e32 v125, 0
	s_waitcnt lgkmcnt(0)
	s_mul_i32 s4, s77, s4
	s_mul_i32 s0, s4, s76
	v_writelane_b32 v242, s0, 7
	s_movk_i32 s77, 0x1000
	v_readlane_b32 s14, v242, 0
	s_cmpk_lt_i32 s14, 0x200
	s_cselect_b64 s[0:1], -1, 0
	v_writelane_b32 v242, s0, 8
	s_cmpk_lg_i32 s76, 0x200
	s_movk_i32 s80, 0x60
	v_writelane_b32 v242, s1, 9
	s_cselect_b64 s[0:1], -1, 0
	v_writelane_b32 v242, s0, 10
	s_cmpk_gt_i32 s14, 0xff
	s_mov_b64 s[40:41], 0x100
	v_writelane_b32 v242, s1, 11
	s_cselect_b64 s[0:1], -1, 0
	v_writelane_b32 v242, s0, 12
	s_lshl_b32 s4, s14, 1
	s_movk_i32 s33, 0x7fff
	v_writelane_b32 v242, s1, 13
	s_add_i32 s0, s4, 0xffffff00
	s_cmpk_lt_i32 s14, 0x600
	v_writelane_b32 v242, s0, 14
	s_cselect_b64 s[0:1], -1, 0
	v_writelane_b32 v242, s0, 15
	s_cmpk_lt_i32 s14, 0x300
	s_mov_b64 s[82:83], 0x68f6080
	v_writelane_b32 v242, s1, 16
	s_cselect_b64 s[0:1], -1, 0
	v_writelane_b32 v242, s0, 17
	s_mov_b64 s[84:85], 0x68f6100
	s_mov_b64 s[86:87], 0xb36080
	v_writelane_b32 v242, s1, 18
	s_not_b32 s0, s14
	s_cmpk_lt_i32 s14, 0x3c0
	v_writelane_b32 v242, s0, 19
	s_cselect_b64 s[0:1], -1, 0
	v_writelane_b32 v242, s0, 20
	s_cmpk_lt_i32 s14, 0x580
	s_mov_b64 s[88:89], 0xb36100
	v_writelane_b32 v242, s1, 21
	s_cselect_b64 s[0:1], -1, 0
	v_writelane_b32 v242, s0, 22
	s_mov_b32 s81, 0xffff0000
	s_mov_b64 s[90:91], 0x400
	v_writelane_b32 v242, s1, 23
	s_lshl_b32 s0, s76, 2
	v_writelane_b32 v242, s0, 24
	s_lshl_b32 s0, s14, 2
	s_cmpk_lt_i32 s14, 0xc0
	v_writelane_b32 v242, s0, 25
	s_cselect_b64 s[0:1], -1, 0
	v_writelane_b32 v242, s0, 26
	s_cmpk_lt_i32 s14, 0x120
	s_movk_i32 s92, 0x2400
	v_writelane_b32 v242, s1, 27
	s_cselect_b64 s[0:1], -1, 0
	v_writelane_b32 v242, s0, 28
	s_cmp_lt_i32 s14, 32
	s_mov_b32 s93, 0xf149f2ca
	v_writelane_b32 v242, s1, 29
	s_cselect_b64 s[0:1], -1, 0
	v_writelane_b32 v242, s0, 30
	s_cmpk_lt_i32 s76, 0x161
	s_mov_b32 s94, 0x7f800000
	v_writelane_b32 v242, s1, 31
	s_cselect_b64 s[0:1], -1, 0
	v_writelane_b32 v242, s0, 32
	s_cmpk_lt_i32 s14, 0x2e0
	v_mov_b32_e32 v157, 0x3ecc95a3
	v_writelane_b32 v242, s1, 33
	s_cselect_b64 s[0:1], -1, 0
	s_add_i32 s4, s14, 0x1000
	s_cmpk_lt_i32 s14, 0x2c0
	s_cselect_b32 s5, s14, s4
	v_writelane_b32 v242, s0, 34
	s_cmpk_gt_i32 s5, 0xaff
	v_sub_co_u32_e32 v2, vcc, s5, v1
	v_writelane_b32 v242, s1, 35
	s_cselect_b64 s[0:1], -1, 0
	v_writelane_b32 v242, s0, 36
	s_cmpk_gt_u32 s5, 0x107f
	v_readfirstlane_b32 s4, v2
	v_writelane_b32 v242, s1, 37
	s_cselect_b64 s[0:1], -1, 0
	v_writelane_b32 v242, s0, 38
	s_cmpk_gt_u32 s5, 0x11bf
	v_lshrrev_b32_e32 v2, 20, v0
	v_writelane_b32 v242, s1, 39
	s_cselect_b64 s[0:1], -1, 0
	v_writelane_b32 v242, s0, 40
	s_cmpk_gt_u32 s5, 0x123f
	v_lshrrev_b32_e32 v0, 10, v0
	v_writelane_b32 v242, s1, 41
	s_cselect_b64 s[0:1], -1, 0
	v_writelane_b32 v242, s0, 42
	s_lshr_b32 s78, s4, 4
	s_lshl_b32 s4, s5, 4
	v_writelane_b32 v242, s1, 43
	s_xor_b64 s[0:1], vcc, -1
	v_writelane_b32 v242, s0, 44
	s_lshl_b32 s6, s5, 3
	s_add_i32 s7, s6, 0x7fff6e00
	v_writelane_b32 v242, s1, 45
	s_lshl_b64 s[0:1], s[78:79], 19
	v_writelane_b32 v242, s0, 46
	s_add_i32 s6, s6, 0x7fff7200
	v_or_b32_e32 v0, v0, v2
	v_writelane_b32 v242, s1, 47
	s_lshl_b64 s[0:1], s[78:79], 18
	v_writelane_b32 v242, s0, 48
	v_mov_b32_e32 v158, 0x3c088889
	s_mov_b32 s95, 0xbe99999a
	v_writelane_b32 v242, s1, 49
	s_and_b32 s0, s4, 0xc0
	s_lshl_b32 s4, s5, 7
	v_writelane_b32 v242, s0, 50
	s_and_b32 s0, s4, 0x180
	v_writelane_b32 v242, s0, 51
	s_and_b32 s0, s7, 0x7fffffc0
	v_writelane_b32 v242, s0, 52
	s_and_b32 s0, s4, 0x380
	s_add_i32 s4, s5, 0xef80
	v_writelane_b32 v242, s0, 53
	s_and_b32 s0, s6, 0x7fffffc0
	s_and_b32 s6, s4, 0xffff
	s_mul_i32 s6, s6, 0xcccd
	s_lshr_b32 s6, s6, 20
	v_writelane_b32 v242, s0, 54
	s_lshl_b32 s0, s6, 6
	s_mul_i32 s6, s6, 20
	s_sub_i32 s4, s4, s6
	s_lshl_b32 s4, s4, 7
	v_writelane_b32 v242, s0, 55
	s_and_b32 s0, s4, 0xff80
	s_add_i32 s4, s5, 0xf500
	s_and_b32 s6, s4, 0xffff
	s_mul_i32 s6, s6, 0xba2f
	s_lshr_b32 s7, s6, 24
	s_mul_i32 s9, s7, 0x160
	s_sub_i32 s9, s4, s9
	s_lshr_b32 s6, s6, 25
	v_writelane_b32 v242, s0, 56
	s_bitcmp0_b32 s7, 0
	s_mul_i32 s0, s6, 0xb00000
	s_cselect_b32 s4, 13, 16
	v_writelane_b32 v242, s0, 57
	s_mul_i32 s0, s7, 0x580000
	s_lshl_b32 s6, s9, 3
	v_writelane_b32 v242, s0, 58
	s_and_b32 s0, s6, 0xfc0
	s_lshl_b32 s6, s9, 7
	v_writelane_b32 v242, s0, 59
	s_and_b32 s0, s6, 0x380
	s_mul_hi_i32 s6, s5, 0x2e8ba2e9
	s_lshr_b32 s7, s6, 31
	s_ashr_i32 s6, s6, 7
	s_add_i32 s6, s6, s7
	s_mul_i32 s7, s6, 0x2c0
	s_sub_i32 s5, s5, s7
	s_sext_i32_i16 s7, s5
	s_mulk_i32 s7, 0xba3
	s_lshr_b32 s9, s7, 31
	s_ashr_i32 s7, s7, 20
	s_ashr_i32 s10, s6, 1
	v_writelane_b32 v242, s0, 60
	s_add_i32 s7, s7, s9
	s_mul_hi_i32 s0, s10, 0xb00000
	s_mul_i32 s9, s7, 0x160
	v_writelane_b32 v242, s0, 61
	s_mul_i32 s0, s10, 0xb00000
	s_sub_i32 s9, s5, s9
	s_and_b32 s11, s6, 1
	s_addk_i32 s5, 0x15f
	v_writelane_b32 v242, s0, 62
	s_mul_hi_i32 s0, s6, 0xb00000
	s_cmpk_lt_u32 s5, 0x2bf
	v_writelane_b32 v242, s0, 63
	s_mul_i32 s0, s6, 0xb00000
	s_sext_i32_i16 s6, s9
	s_cselect_b32 s5, 11, 12
	s_cselect_b32 s12, 14, 15
	s_cmp_eq_u32 s11, 0
	s_mulk_i32 s6, 0xba3
	s_cselect_b32 s5, s5, s12
	s_lshr_b32 s10, s6, 31
	s_lshr_b32 s6, s6, 16
	s_add_i32 s6, s6, s10
	s_sext_i32_i16 s10, s6
	s_mul_i32 s6, s6, 22
	s_sub_i32 s6, s9, s6
	v_writelane_b32 v241, s0, 0
	s_lshl_b32 s0, s10, 6
	s_sext_i32_i16 s6, s6
	v_writelane_b32 v241, s0, 1
	s_lshl_b32 s0, s6, 7
	s_add_i32 s7, s7, 1
	v_writelane_b32 v241, s0, 2
	s_and_b32 s0, s7, 0xffff
	s_cmpk_gt_i32 s14, 0x11f
	v_writelane_b32 v241, s0, 3
	s_cselect_b64 s[0:1], -1, 0
	v_writelane_b32 v241, s0, 4
	s_add_i32 s7, s14, 0xfffffee0
	v_mov_b32_e32 v159, 0x3ab69700
	v_writelane_b32 v241, s1, 5
	s_add_i32 s0, s76, 0xfffffee0
	s_cmpk_lt_u32 s7, 0x2e0
	v_writelane_b32 v241, s0, 6
	s_cselect_b64 s[0:1], -1, 0
	v_writelane_b32 v241, s0, 7
	s_cmpk_gt_u32 s7, 0x2bf
	s_mov_b32 s96, 0x43000000
	v_writelane_b32 v241, s1, 8
	s_cselect_b64 s[0:1], -1, 0
	s_add_i32 s9, s14, 0xfffffc20
	v_writelane_b32 v241, s0, 9
	s_lshr_b32 s78, s9, 4
	s_add_i32 s6, s14, 0xee0
	v_writelane_b32 v241, s1, 10
	s_lshl_b64 s[0:1], s[78:79], 19
	v_writelane_b32 v241, s0, 11
	s_lshl_b32 s9, s6, 4
	s_lshl_b32 s6, s6, 7
	v_writelane_b32 v241, s1, 12
	s_lshl_b64 s[0:1], s[78:79], 18
	v_writelane_b32 v241, s0, 13
	s_mov_b32 s97, 0xc1880000
	v_mov_b32_e32 v160, 0x260
	v_writelane_b32 v241, s1, 14
	s_and_b32 s0, s9, 0xc0
	v_writelane_b32 v241, s0, 15
	s_and_b32 s0, s6, 0x180
	s_add_i32 s6, s14, 0xfd80
	s_cmpk_lt_u32 s7, 0x160
	s_cselect_b32 s9, s7, s6
	s_cselect_b32 s6, 11, 12
	s_and_b32 s10, s9, 0xffff
	s_mul_i32 s10, s10, 0xba2f
	s_lshr_b32 s11, s10, 20
	s_mul_i32 s11, s11, 22
	s_lshr_b32 s10, s10, 14
	s_sub_i32 s9, s9, s11
	v_writelane_b32 v241, s0, 16
	s_and_b32 s0, s10, 0xffc0
	s_lshl_b32 s9, s9, 7
	v_writelane_b32 v241, s0, 17
	s_and_b32 s0, s9, 0xff80
	s_cmpk_gt_u32 s7, 0x15f
	s_movk_i32 s7, 0x3ff
	v_writelane_b32 v241, s0, 18
	s_cselect_b32 s0, 2, 1
	v_and_or_b32 v0, v0, s7, v127
	v_writelane_b32 v241, s0, 19
	v_cmp_eq_u32_e64 s[10:11], 0, v0
	s_lshl_b32 s0, s14, 8
	s_lshl_b32 s25, s76, 8
	v_writelane_b32 v241, s10, 20
	s_mov_b32 s24, s25
	s_mov_b32 s1, -1
	v_writelane_b32 v241, s11, 21
	s_add_u32 s10, s16, 0xdeb6200
	s_addc_u32 s11, s17, 0
	v_writelane_b32 v241, s10, 22
	s_mov_b64 s[54:55], 0x10eba080
	s_mov_b64 s[64:65], 0x4236080
	v_writelane_b32 v241, s11, 23
	s_add_u32 s10, s16, 0xdeb6400
	s_addc_u32 s11, s17, 0
	v_writelane_b32 v241, s10, 24
	v_mov_b32_e32 v161, 0x3ca908c9
	v_mov_b32_e32 v126, 0x358637bd
	v_writelane_b32 v241, s11, 25
	s_add_u32 s10, s16, 0xdeb6500
	s_addc_u32 s11, s17, 0
	v_writelane_b32 v241, s10, 26
	s_mov_b32 s68, 0x800000
	s_mov_b32 s69, 0x7060302
	v_writelane_b32 v241, s11, 27
	s_add_u32 s10, s16, 0xdeb6600
	s_addc_u32 s11, s17, 0
	v_writelane_b32 v241, s10, 28
	v_mov_b32_e32 v163, 0xbf1f24be
	v_mov_b32_e32 v164, 0x3e642e9d
	v_writelane_b32 v241, s11, 29
	s_add_u32 s10, s16, 0xdeb6700
	s_addc_u32 s11, s17, 0
	v_writelane_b32 v241, s10, 30
	v_mov_b32_e32 v165, 0x13ff0
	v_mov_b32_e32 v166, 0x13ff4
	v_writelane_b32 v241, s11, 31
	s_add_u32 s10, s16, 0xdeb6800
	s_addc_u32 s11, s17, 0
	v_writelane_b32 v241, s10, 32
	v_mov_b32_e32 v167, 1
	v_mov_b32_e32 v168, 0x200
	v_writelane_b32 v241, s11, 33
	s_add_u32 s10, s16, 0xdeb6900
	s_addc_u32 s11, s17, 0
	v_writelane_b32 v241, s10, 34
	v_mov_b32_e32 v169, 0xb400
	v_mov_b32_e32 v170, 0x7f800000
	v_writelane_b32 v241, s11, 35
	s_add_u32 s10, s16, 0xdeb6a00
	s_addc_u32 s11, s17, 0
	v_writelane_b32 v241, s10, 36
	v_mov_b32_e32 v128, 0x3f317218
	v_mov_b32_e32 v171, 0x7f000000
	v_writelane_b32 v241, s11, 37
	s_add_u32 s10, s16, 0xdeb6b00
	s_addc_u32 s11, s17, 0
	v_writelane_b32 v241, s10, 38
	v_mov_b32_e32 v172, 0x10400
	v_mov_b32_e32 v173, 0x10500
	v_writelane_b32 v241, s11, 39
	s_add_u32 s10, s16, 0xdeb6c00
	s_addc_u32 s11, s17, 0
	v_writelane_b32 v241, s10, 40
	v_mov_b32_e32 v174, 0x10600
	v_mov_b32_e32 v175, 0x10700
	v_writelane_b32 v241, s11, 41
	s_add_u32 s10, s16, 0xdeb6d00
	s_addc_u32 s11, s17, 0
	v_writelane_b32 v241, s10, 42
	v_mov_b32_e32 v176, 0x3e000000
	v_mov_b32_e32 v177, 0x3ff
	v_writelane_b32 v241, s11, 43
	s_add_u32 s10, s16, 0xdeb6e00
	s_addc_u32 s11, s17, 0
	v_writelane_b32 v241, s10, 44
	v_mov_b32_e32 v178, 0x7fc00000
	v_mov_b32_e32 v179, 0xffc00000
	v_writelane_b32 v241, s11, 45
	s_add_u32 s10, s16, 0xdeb6f00
	s_addc_u32 s11, s17, 0
	v_writelane_b32 v241, s10, 46
	v_mov_b32_e32 v181, 0
	v_mov_b32_e32 v180, 0
	v_writelane_b32 v241, s11, 47
	s_add_u32 s10, s16, 0xdeb7000
	s_addc_u32 s11, s17, 0
	v_writelane_b32 v241, s10, 48
	s_nop 1
	v_writelane_b32 v241, s11, 49
	s_add_u32 s10, s16, 0xdeb7100
	s_addc_u32 s11, s17, 0
	v_writelane_b32 v241, s10, 50
	s_nop 1
	v_writelane_b32 v241, s11, 51
	s_add_u32 s10, s16, 0xdeb7200
	s_addc_u32 s11, s17, 0
	v_writelane_b32 v241, s10, 52
	s_nop 1
	v_writelane_b32 v241, s11, 53
	s_add_u32 s10, s16, 0xdeb7300
	s_addc_u32 s11, s17, 0
	v_writelane_b32 v241, s10, 54
	s_cmp_eq_u32 s8, 15
	s_nop 0
	v_writelane_b32 v241, s11, 55
	s_cselect_b64 s[10:11], -1, 0
	v_writelane_b32 v241, s10, 56
	s_cmp_eq_u32 s8, 14
	s_nop 0
	v_writelane_b32 v241, s11, 57
	s_cselect_b64 s[10:11], -1, 0
	v_writelane_b32 v241, s10, 58
	s_cmp_eq_u32 s8, 13
	s_nop 0
	v_writelane_b32 v241, s11, 59
	s_cselect_b64 s[10:11], -1, 0
	v_writelane_b32 v241, s10, 60
	s_cmp_eq_u32 s8, 12
	s_nop 0
	v_writelane_b32 v241, s11, 61
	s_cselect_b64 s[10:11], -1, 0
	v_writelane_b32 v241, s10, 62
	s_cmp_eq_u32 s8, 11
	s_nop 0
	v_writelane_b32 v241, s11, 63
	s_cselect_b64 s[10:11], -1, 0
	v_writelane_b32 v240, s10, 0
	s_cmp_eq_u32 s8, 10
	s_nop 0
	v_writelane_b32 v240, s11, 1
	s_cselect_b64 s[10:11], -1, 0
	v_writelane_b32 v240, s10, 2
	s_cmp_eq_u32 s8, 9
	s_nop 0
	v_writelane_b32 v240, s11, 3
	s_cselect_b64 s[10:11], -1, 0
	v_writelane_b32 v240, s10, 4
	s_cmp_eq_u32 s8, 8
	s_nop 0
	v_writelane_b32 v240, s11, 5
	s_cselect_b64 s[10:11], -1, 0
	v_writelane_b32 v240, s10, 6
	s_cmp_eq_u32 s8, 7
	s_nop 0
	v_writelane_b32 v240, s11, 7
	s_cselect_b64 s[10:11], -1, 0
	v_writelane_b32 v240, s10, 8
	s_cmp_eq_u32 s8, 6
	s_nop 0
	v_writelane_b32 v240, s11, 9
	s_cselect_b64 s[10:11], -1, 0
	v_writelane_b32 v240, s10, 10
	s_cmp_eq_u32 s8, 5
	s_nop 0
	v_writelane_b32 v240, s11, 11
	s_cselect_b64 s[10:11], -1, 0
	v_writelane_b32 v240, s10, 12
	s_cmp_eq_u32 s8, 4
	s_nop 0
	v_writelane_b32 v240, s11, 13
	s_cselect_b64 s[10:11], -1, 0
	v_writelane_b32 v240, s10, 14
	s_cmp_eq_u32 s8, 3
	s_nop 0
	v_writelane_b32 v240, s11, 15
	s_cselect_b64 s[10:11], -1, 0
	v_writelane_b32 v240, s10, 16
	s_cmp_eq_u32 s8, 2
	s_nop 0
	v_writelane_b32 v240, s11, 17
	s_cselect_b64 s[10:11], -1, 0
	v_writelane_b32 v240, s10, 18
	s_cmp_eq_u32 s8, 1
	s_nop 0
	v_writelane_b32 v240, s11, 19
	s_cselect_b64 s[10:11], -1, 0
	v_writelane_b32 v240, s10, 20
	s_cmp_eq_u32 s8, 0
	s_nop 0
	v_writelane_b32 v240, s11, 21
	s_cselect_b64 s[10:11], -1, 0
	s_lshl_b32 s7, s8, 8
	s_add_u32 s2, s2, s7
	s_addc_u32 s3, s3, 0
	v_writelane_b32 v240, s10, 22
	s_add_u32 s8, s2, 0x1400
	s_addc_u32 s9, s3, 0
	v_writelane_b32 v240, s11, 23
	v_writelane_b32 v240, s8, 24
	s_add_u32 s2, s2, 0x2400
	s_addc_u32 s3, s3, 0
	v_writelane_b32 v240, s9, 25
	v_writelane_b32 v240, s2, 26
	s_nop 1
	v_writelane_b32 v240, s3, 27
	s_add_u32 s2, s16, 0xdeb9400
	s_addc_u32 s3, s17, 0
	v_writelane_b32 v240, s2, 28
	s_nop 1
	v_writelane_b32 v240, s3, 29
	s_add_u32 s2, s16, 0xdeb9500
	s_addc_u32 s3, s17, 0
	v_writelane_b32 v240, s2, 30
	s_nop 1
	v_writelane_b32 v240, s3, 31
	v_writelane_b32 v238, 0, 62
	v_writelane_b32 v240, s0, 32
	s_add_i32 s0, s25, s0
	v_writelane_b32 v240, s0, 33
	s_mul_i32 s0, s76, 0x300
	v_writelane_b32 v240, s0, 34
	s_lshl_b32 s0, s76, 10
	v_writelane_b32 v240, s0, 35
	v_writelane_b32 v240, s0, 36
	v_writelane_b32 v240, s0, 37
	v_writelane_b32 v240, s0, 38
	s_mov_b32 s0, s79
	s_and_b64 s[0:1], s[24:25], s[0:1]
	v_writelane_b32 v240, s0, 39
	s_lshl_b32 s2, s76, 9
	s_nop 0
	v_writelane_b32 v240, s1, 40
	v_writelane_b32 v240, s2, 41
	v_writelane_b32 v240, s2, 42
	v_writelane_b32 v240, s2, 43
	s_abs_i32 s2, s76
	v_cvt_f32_u32_e32 v0, s2
	s_sub_i32 s0, 0, s2
	v_rcp_iflag_f32_e32 v0, v0
	s_nop 0
	v_mul_f32_e32 v0, 0x4f7ffffe, v0
	v_cvt_u32_f32_e32 v0, v0
	s_nop 0
	v_readfirstlane_b32 s1, v0
	s_mul_i32 s0, s0, s1
	s_mul_hi_u32 s0, s1, s0
	s_add_i32 s3, s1, s0
	s_mul_hi_u32 s0, s3, 0x3c0
	s_mul_i32 s0, s0, s2
	s_sub_i32 s0, 0x3c0, s0
	s_sub_i32 s1, s0, s2
	s_cmp_ge_u32 s0, s2
	s_cselect_b32 s0, s1, s0
	s_sub_i32 s1, s0, s2
	s_cmp_ge_u32 s0, s2
	s_cselect_b32 s7, s1, s0
	s_cmp_ge_i32 s14, s7
	s_cselect_b64 s[0:1], -1, 0
	v_writelane_b32 v240, s0, 44
	s_mul_hi_u32 s3, s3, 0x580
	s_mul_i32 s3, s3, s2
	v_writelane_b32 v240, s1, 45
	s_sub_i32 s0, s14, s7
	s_sub_i32 s1, s76, s7
	s_cmpk_lt_i32 s0, 0x200
	v_writelane_b32 v240, s1, 46
	s_cselect_b64 s[8:9], -1, 0
	s_add_i32 s1, s0, 0xffffff80
	s_cmpk_lt_i32 s0, 0x80
	s_cselect_b32 s0, s0, s1
	s_movk_i32 s1, 0x11c0
	s_cselect_b32 s1, s1, 0x2c0
	s_add_i32 s1, s1, s0
	v_writelane_b32 v240, s8, 47
	s_cmpk_gt_i32 s1, 0xaff
	v_sub_co_u32_e32 v0, vcc, s1, v1
	v_writelane_b32 v240, s9, 48
	s_cselect_b64 s[8:9], -1, 0
	v_writelane_b32 v240, s8, 49
	s_cmpk_gt_u32 s1, 0x107f
	v_readfirstlane_b32 s0, v0
	v_writelane_b32 v240, s9, 50
	s_cselect_b64 s[8:9], -1, 0
	v_writelane_b32 v240, s8, 51
	s_cmpk_gt_u32 s1, 0x11bf
	v_cvt_f32_u32_e32 v0, s25
	v_writelane_b32 v240, s9, 52
	s_cselect_b64 s[8:9], -1, 0
	v_writelane_b32 v240, s8, 53
	s_cmpk_gt_u32 s1, 0x123f
	v_rcp_iflag_f32_e32 v0, v0
	v_writelane_b32 v240, s9, 54
	s_cselect_b64 s[8:9], -1, 0
	v_writelane_b32 v240, s8, 55
	s_lshr_b32 s78, s0, 4
	s_lshl_b32 s0, s1, 4
	v_writelane_b32 v240, s9, 56
	s_xor_b64 s[8:9], vcc, -1
	v_writelane_b32 v240, s8, 57
	s_and_b32 s0, s0, 0xc0
	v_mul_f32_e32 v0, 0x4f7ffffe, v0
	v_writelane_b32 v240, s9, 58
	s_lshl_b64 s[8:9], s[78:79], 19
	v_writelane_b32 v240, s8, 59
	v_cvt_u32_f32_e32 v0, v0
	s_nop 0
	v_writelane_b32 v240, s9, 60
	s_lshl_b64 s[8:9], s[78:79], 18
	v_writelane_b32 v240, s8, 61
	s_nop 1
	v_writelane_b32 v240, s9, 62
	v_writelane_b32 v240, s0, 63
	s_lshl_b32 s0, s1, 7
	s_and_b32 s8, s0, 0x180
	v_writelane_b32 v239, s8, 0
	s_lshl_b32 s8, s1, 3
	s_add_i32 s9, s8, 0x7fff6e00
	s_and_b32 s9, s9, 0x7fffffc0
	v_writelane_b32 v239, s9, 1
	s_and_b32 s0, s0, 0x380
	s_add_i32 s8, s8, 0x7fff7200
	v_writelane_b32 v239, s0, 2
	s_and_b32 s0, s8, 0x7fffffc0
	v_writelane_b32 v239, s0, 3
	s_add_i32 s0, s1, 0xef80
	s_and_b32 s8, s0, 0xffff
	s_mul_i32 s8, s8, 0xcccd
	s_lshr_b32 s8, s8, 20
	s_lshl_b32 s9, s8, 6
	s_mul_i32 s8, s8, 20
	s_sub_i32 s0, s0, s8
	s_lshl_b32 s0, s0, 7
	v_writelane_b32 v239, s9, 4
	s_and_b32 s0, s0, 0xff80
	v_writelane_b32 v239, s0, 5
	s_add_i32 s0, s1, 0xf500
	s_and_b32 s8, s0, 0xffff
	s_mul_i32 s8, s8, 0xba2f
	s_lshr_b32 s9, s8, 24
	s_mul_i32 s10, s9, 0x160
	s_lshr_b32 s11, s8, 25
	s_sub_i32 s10, s0, s10
	s_bfe_u32 s0, s8, 0x10018
	s_mul_i32 s8, s11, 0xb00000
	s_cmp_eq_u32 s0, 0
	v_writelane_b32 v239, s8, 6
	s_mul_i32 s8, s9, 0x580000
	s_cselect_b32 s0, 13, 16
	v_writelane_b32 v239, s8, 7
	s_lshl_b32 s8, s10, 3
	s_and_b32 s8, s8, 0xfc0
	v_writelane_b32 v239, s8, 8
	s_lshl_b32 s8, s10, 7
	s_and_b32 s8, s8, 0x380
	v_writelane_b32 v239, s8, 9
	s_sext_i32_i16 s8, s1
	s_mulk_i32 s8, 0xba3
	s_lshr_b32 s9, s8, 31
	s_ashr_i32 s8, s8, 21
	s_add_i32 s8, s8, s9
	s_mul_i32 s9, s8, 0x2c0
	s_sub_i32 s1, s1, s9
	s_sext_i32_i16 s9, s1
	s_mulk_i32 s9, 0xba3
	s_lshr_b32 s10, s9, 31
	s_ashr_i32 s9, s9, 20
	s_add_i32 s9, s9, s10
	s_mul_i32 s10, s9, 0x160
	s_sub_i32 s10, s1, s10
	s_addk_i32 s1, 0x15f
	s_bfe_u32 s11, s8, 0xf0001
	s_and_b32 s12, s8, 1
	s_and_b32 s1, s1, 0xffff
	s_cmpk_lt_u32 s1, 0x2bf
	s_cselect_b32 s1, 11, 12
	s_cselect_b32 s13, 14, 15
	s_cmp_eq_u32 s12, 0
	s_mul_hi_u32 s12, s11, 0xb00000
	s_cselect_b32 s1, s1, s13
	v_writelane_b32 v239, s12, 10
	s_mul_i32 s11, s11, 0xb00000
	s_and_b32 s8, s8, 0xffff
	v_writelane_b32 v239, s11, 11
	s_mul_hi_u32 s11, s8, 0xb00000
	v_writelane_b32 v239, s11, 12
	s_mul_i32 s8, s8, 0xb00000
	v_writelane_b32 v239, s8, 13
	s_sext_i32_i16 s8, s10
	s_mulk_i32 s8, 0xba3
	s_lshr_b32 s11, s8, 31
	s_lshr_b32 s8, s8, 16
	s_add_i32 s8, s8, s11
	s_sext_i32_i16 s11, s8
	s_mul_i32 s8, s8, 22
	s_sub_i32 s8, s10, s8
	s_lshl_b32 s11, s11, 6
	s_sext_i32_i16 s8, s8
	v_writelane_b32 v239, s11, 14
	s_lshl_b32 s8, s8, 7
	s_add_i32 s9, s9, 1
	v_writelane_b32 v239, s8, 15
	s_and_b32 s8, s9, 0xffff
	s_sub_i32 s3, 0x580, s3
	v_writelane_b32 v239, s8, 16
	s_sub_i32 s8, s3, s2
	s_cmp_ge_u32 s3, s2
	s_cselect_b32 s3, s8, s3
	s_sub_i32 s8, s3, s2
	s_cmp_ge_u32 s3, s2
	s_cselect_b32 s8, s8, s3
	s_cmp_ge_i32 s14, s8
	s_cselect_b64 s[2:3], -1, 0
	v_writelane_b32 v239, s2, 17
	s_sub_i32 s9, s14, s8
	s_add_i32 s10, s9, 0xfffffea0
	v_writelane_b32 v239, s3, 18
	s_sub_i32 s2, s76, s8
	s_cmpk_lt_i32 s9, 0x160
	v_writelane_b32 v239, s2, 19
	s_cselect_b64 s[2:3], -1, 0
	v_writelane_b32 v239, s2, 20
	s_nop 1
	v_writelane_b32 v239, s3, 21
	s_and_b64 s[2:3], s[2:3], exec
	v_writelane_b32 v239, s9, 22
	v_writelane_b32 v239, s10, 23
	s_cselect_b32 s2, s9, s10
	v_writelane_b32 v239, s2, 24
	s_sub_i32 s2, 0, s25
	v_mul_lo_u32 v1, s2, v0
	s_lshl_b32 s2, s14, 7
	v_writelane_b32 v239, s2, 25
	s_lshl_b32 s2, s76, 7
	v_writelane_b32 v239, s2, 26
	s_lshl_b32 s2, s14, 3
	v_writelane_b32 v239, s2, 27
	s_lshl_b32 s2, s76, 3
	v_writelane_b32 v239, s2, 28
	s_lshl_b32 s2, s14, 4
	v_writelane_b32 v239, s2, 29
	s_lshl_b32 s2, s76, 4
	v_writelane_b32 v239, s2, 30
	s_lshl_b32 s2, s14, 5
	v_writelane_b32 v239, s2, 31
	s_lshl_b32 s2, s76, 5
	v_writelane_b32 v239, s2, 32
	s_lshl_b32 s2, s7, 1
	s_sub_i32 s2, s76, s2
	v_writelane_b32 v239, s2, 33
	s_sub_i32 s2, 0, s7
	v_writelane_b32 v239, s2, 34
	s_lshl_b32 s2, s8, 1
	s_sub_i32 s2, s76, s2
	v_writelane_b32 v239, s2, 35
	s_sub_i32 s2, 0, s8
	s_ashr_i32 s19, s18, 31
	v_writelane_b32 v239, s2, 36
	s_lshl_b64 s[2:3], s[18:19], 12
	v_writelane_b32 v239, s2, 37
	s_mov_b32 s7, s25
	s_lshl_b32 s0, s0, 3
	v_writelane_b32 v239, s3, 38
	s_mov_b32 s2, s18
	v_writelane_b32 v239, s2, 39
	v_mul_hi_u32 v1, v0, v1
	v_add_u32_e32 v156, v0, v1
	v_writelane_b32 v239, s3, 40
	s_lshl_b64 s[2:3], s[18:19], 11
	v_writelane_b32 v239, s2, 41
	v_mbcnt_lo_u32_b32 v0, -1, 0
	s_nop 0
	v_writelane_b32 v239, s3, 42
	s_ashr_i32 s3, s25, 31
	v_writelane_b32 v239, s6, 43
	s_mov_b32 s2, s25
	s_lshl_b64 s[8:9], s[2:3], 1
	v_writelane_b32 v239, s7, 44
	v_writelane_b32 v239, s8, 45
	s_lshl_b64 s[2:3], s[2:3], 2
	v_mbcnt_hi_u32_b32 v162, -1, v0
	v_writelane_b32 v239, s9, 46
	v_writelane_b32 v239, s2, 47
	s_nop 1
	v_writelane_b32 v239, s3, 48
	v_writelane_b32 v239, s0, 49
	s_lshl_b32 s0, s1, 3
	v_writelane_b32 v239, s0, 50
	s_lshl_b32 s0, s4, 3
	v_writelane_b32 v239, s0, 51
	s_lshl_b32 s0, s5, 3
	v_writelane_b32 v239, s0, 52
	s_lshl_b32 s0, s6, 3
	v_writelane_b32 v239, s0, 53
	s_mov_b64 s[2:3], 0x80
	v_writelane_b32 v239, s76, 54
	s_nop 1
	v_writelane_b32 v239, s77, 55
	s_branch .LBB0_11

.LBB0_1464:
	v_readlane_b32 s8, v240, 24
	v_readlane_b32 s9, v240, 25
	v_mov_b32_e32 v3, 1
	v_readlane_b32 s14, v238, 62
	s_nop 4
	global_atomic_add v3, v125, v3, s[8:9] sc0
	s_add_u32 s14, s14, 1
	v_readlane_b32 s10, v240, 26
	v_readlane_b32 s11, v240, 27
	v_writelane_b32 v238, s14, 62
	v_mul_lo_u32 v4, v2, s14
	v_mul_lo_u32 v1, v0, s14
	s_mov_b32 s12, 0
	s_waitcnt vmcnt(0)
	v_add_u32_e32 v3, 1, v3
	v_cmp_ne_u32_e32 vcc, v3, v4
	s_cbranch_vccnz .Lxb_spin
	buffer_wbl2 sc1
	v_readlane_b32 s8, v240, 28
	v_readlane_b32 s9, v240, 29
	s_sub_u32 s8, s8, 0x1000
	s_subb_u32 s9, s9, 0
	s_mov_b64 exec, 0xffff
	v_lshlrev_b32_e32 v5, 8, v127
	v_mov_b32_e32 v3, 1
	s_waitcnt vmcnt(0)
	global_atomic_add v5, v3, s[8:9]
	s_mov_b64 exec, 1
.Lxb_spin:
	global_load_dword v3, v125, s[10:11] sc1
	s_waitcnt vmcnt(0)
	v_cmp_lt_u32_e32 vcc, v3, v1
	s_cbranch_vccz .Lxb_go
	s_sleep 1
	s_add_u32 s12, s12, 1
	s_cmp_lt_u32 s12, 0x40000
	s_cbranch_scc1 .Lxb_spin
	v_readlane_b32 s8, v241, 22
	v_readlane_b32 s9, v241, 23
	v_mov_b32_e32 v3, 1
	s_nop 3
	global_atomic_add v125, v3, s[8:9]
.Lxb_go:
	s_cmp_eq_u32 s16, 8
	s_cbranch_scc1 .Lxb_acq
	s_cmp_eq_u32 s16, 11
	s_cbranch_scc1 .Lxb_acq
	s_cmp_eq_u32 s16, 14
	s_cbranch_scc1 .Lxb_acq
	s_cmp_lg_u32 s16, 18
	s_cbranch_scc1 .Lxb_out

.Lxb_out:
	s_waitcnt vmcnt(0)
	s_getpc_b64 s[98:99]
